# barriers: no vmcnt drain before/after the XCD generation-word publish on the last arriver's path
# baseline (speedup 1.0000x reference)
; __device__ __forceinline__ unsigned xb_ld(unsigned* p)              { return __hip_atomic_load(p, __ATOMIC_RELAXED, __HIP_MEMORY_SCOPE_AGENT); }
; __device__ __forceinline__ unsigned xb_add(unsigned* p, unsigned v) { return __hip_atomic_fetch_add(p, v, __ATOMIC_RELAXED, __HIP_MEMORY_SCOPE_AGENT); }
; #define XB_SPIN(cond, bar) do { unsigned _sp = 0; while (cond) { __builtin_amdgcn_s_sleep(1); \
;     if ((++_sp & 255u) == 0u) { if (xb_ld(&(bar)[XB_TMO])) break; if (_sp > XB_SPIN_CAP) { atomicAdd(&(bar)[XB_TMO], 1u); break; } } } } while (0)
; __device__ __forceinline__ void xcd_barrier(const XcdBarrier& b) {
;     ...
;             const unsigned og = xb_add(&bar[XB_TOP], 1u);
;             const unsigned tg = og / nx;
;             if (og + 1u == (tg + 1u) * nx) xb_add(&bar[XB_TOPGEN], 1u);
;             else XB_SPIN(xb_ld(&bar[XB_TOPGEN]) == tg, bar);
;             __builtin_amdgcn_fence(__ATOMIC_ACQUIRE, "agent");
;             xb_add(&bar[XB_XGEN(b.x)], 1u);
;             asm volatile("s_waitcnt vmcnt(0)" ::: "memory");
.LBB0_151:
	s_or_b64 exec, exec, s[8:9]
	s_mov_b64 s[8:9], exec
	v_mbcnt_lo_u32_b32 v0, s8, 0
	v_mbcnt_hi_u32_b32 v0, s9, v0
	v_cmp_eq_u32_e32 vcc, 0, v0
	s_and_saveexec_b64 s[38:39], vcc
	s_cbranch_execz .LBB0_153
	s_bcnt1_i32_b64 s8, s[8:9]
	v_mov_b32_e32 v0, 0x2000
	v_mov_b32_e32 v1, s8
	global_atomic_add v0, v1, s[6:7] offset:1024
.LBB0_153:
	s_or_b64 exec, exec, s[38:39]
.LBB0_154:
	s_or_b64 exec, exec, s[4:5]
	s_waitcnt lgkmcnt(0)
	s_barrier

; __device__ __forceinline__ void xcd_barrier(const XcdBarrier& b) {
;     ...
;             asm volatile("s_waitcnt vmcnt(0)" ::: "memory");
.LBB0_276:
	s_or_b64 exec, exec, s[38:39]
.LBB0_277:
	s_or_b64 exec, exec, s[4:5]
	s_waitcnt lgkmcnt(0)
	s_barrier

; __device__ __forceinline__ unsigned xb_ld(unsigned* p)              { return __hip_atomic_load(p, __ATOMIC_RELAXED, __HIP_MEMORY_SCOPE_AGENT); }
; __device__ __forceinline__ unsigned xb_add(unsigned* p, unsigned v) { return __hip_atomic_fetch_add(p, v, __ATOMIC_RELAXED, __HIP_MEMORY_SCOPE_AGENT); }
; #define XB_SPIN(cond, bar) do { unsigned _sp = 0; while (cond) { __builtin_amdgcn_s_sleep(1); \
;     if ((++_sp & 255u) == 0u) { if (xb_ld(&(bar)[XB_TMO])) break; if (_sp > XB_SPIN_CAP) { atomicAdd(&(bar)[XB_TMO], 1u); break; } } } } while (0)
; __device__ __forceinline__ void xcd_barrier(const XcdBarrier& b) {
;     ...
;             const unsigned og = xb_add(&bar[XB_TOP], 1u);
;             const unsigned tg = og / nx;
;             if (og + 1u == (tg + 1u) * nx) xb_add(&bar[XB_TOPGEN], 1u);
;             else XB_SPIN(xb_ld(&bar[XB_TOPGEN]) == tg, bar);
;             __builtin_amdgcn_fence(__ATOMIC_ACQUIRE, "agent");
;             xb_add(&bar[XB_XGEN(b.x)], 1u);
;             asm volatile("s_waitcnt vmcnt(0)" ::: "memory");
.LBB0_398:
	s_or_b64 exec, exec, s[8:9]
	s_mov_b64 s[8:9], exec
	v_mbcnt_lo_u32_b32 v0, s8, 0
	v_mbcnt_hi_u32_b32 v0, s9, v0
	v_cmp_eq_u32_e32 vcc, 0, v0
	s_and_saveexec_b64 s[12:13], vcc
	s_cbranch_execz .LBB0_400
	s_bcnt1_i32_b64 s8, s[8:9]
	v_mov_b32_e32 v0, 0x2000
	v_mov_b32_e32 v1, s8
	global_atomic_add v0, v1, s[6:7] offset:1024
.LBB0_400:
	s_or_b64 exec, exec, s[12:13]
.LBB0_401:
	s_or_b64 exec, exec, s[4:5]
	s_waitcnt lgkmcnt(0)
	s_barrier

; __device__ __forceinline__ void xcd_barrier(const XcdBarrier& b) {
;     ...
;             asm volatile("s_waitcnt vmcnt(0)" ::: "memory");
.LBB0_465:
	s_or_b64 exec, exec, s[12:13]
.LBB0_466:
	s_or_b64 exec, exec, s[4:5]
	s_mov_b64 s[4:5], 0
	s_waitcnt lgkmcnt(0)
	s_barrier

; __device__ __forceinline__ unsigned xb_add(unsigned* p, unsigned v) { return __hip_atomic_fetch_add(p, v, __ATOMIC_RELAXED, __HIP_MEMORY_SCOPE_AGENT); }
; __device__ __forceinline__ void xcd_barrier(const XcdBarrier& b) {
;     ...
;             xb_add(&bar[XB_XGEN(b.x)], 1u);
;             asm volatile("s_waitcnt vmcnt(0)" ::: "memory");
.Lgb_skip_0:
	v_mov_b32_e32 v0, 0x2000
	v_mov_b32_e32 v1, 1
	global_atomic_add v0, v1, s[6:7] offset:1024

; __device__ __forceinline__ unsigned xb_ld(unsigned* p)              { return __hip_atomic_load(p, __ATOMIC_RELAXED, __HIP_MEMORY_SCOPE_AGENT); }
; __device__ __forceinline__ unsigned xb_add(unsigned* p, unsigned v) { return __hip_atomic_fetch_add(p, v, __ATOMIC_RELAXED, __HIP_MEMORY_SCOPE_AGENT); }
; #define XB_SPIN(cond, bar) do { unsigned _sp = 0; while (cond) { __builtin_amdgcn_s_sleep(1); \
;     if ((++_sp & 255u) == 0u) { if (xb_ld(&(bar)[XB_TMO])) break; if (_sp > XB_SPIN_CAP) { atomicAdd(&(bar)[XB_TMO], 1u); break; } } } } while (0)
; __device__ __forceinline__ void xcd_barrier(const XcdBarrier& b) {
;     ...
;             const unsigned og = xb_add(&bar[XB_TOP], 1u);
;             const unsigned tg = og / nx;
;             if (og + 1u == (tg + 1u) * nx) xb_add(&bar[XB_TOPGEN], 1u);
;             else XB_SPIN(xb_ld(&bar[XB_TOPGEN]) == tg, bar);
;             __builtin_amdgcn_fence(__ATOMIC_ACQUIRE, "agent");
;             xb_add(&bar[XB_XGEN(b.x)], 1u);
;             asm volatile("s_waitcnt vmcnt(0)" ::: "memory");
.LBB0_667:
	s_or_b64 exec, exec, s[12:13]
	s_mov_b64 s[12:13], exec
	v_mbcnt_lo_u32_b32 v0, s12, 0
	v_mbcnt_hi_u32_b32 v0, s13, v0
	v_cmp_eq_u32_e32 vcc, 0, v0
	s_and_saveexec_b64 s[16:17], vcc
	s_cbranch_execz .LBB0_669
	s_bcnt1_i32_b64 s10, s[12:13]
	v_mov_b32_e32 v0, 0x2000
	v_mov_b32_e32 v1, s10
	global_atomic_add v0, v1, s[8:9] offset:1024
.LBB0_669:
	s_or_b64 exec, exec, s[16:17]
.LBB0_670:
	s_or_b64 exec, exec, s[6:7]
	s_waitcnt lgkmcnt(0)
	s_barrier

; __device__ __forceinline__ void xcd_barrier(const XcdBarrier& b) {
;     ...
;             asm volatile("s_waitcnt vmcnt(0)" ::: "memory");
.LBB0_781:
	s_or_b64 exec, exec, s[16:17]
.LBB0_782:
	s_or_b64 exec, exec, s[6:7]
	s_waitcnt lgkmcnt(0)
	s_barrier
	s_mov_b64 s[6:7], -1
	s_and_b64 vcc, exec, s[0:1]
	s_cbranch_vccnz .LBB0_697
	s_branch .LBB0_789

; __device__ __forceinline__ unsigned xb_add(unsigned* p, unsigned v) { return __hip_atomic_fetch_add(p, v, __ATOMIC_RELAXED, __HIP_MEMORY_SCOPE_AGENT); }
; __device__ __forceinline__ void xcd_barrier(const XcdBarrier& b) {
;     ...
;             xb_add(&bar[XB_XGEN(b.x)], 1u);
;             asm volatile("s_waitcnt vmcnt(0)" ::: "memory");
.Lgb_skip_1:
	v_mov_b32_e32 v0, 0x2000
	v_mov_b32_e32 v1, 1
	global_atomic_add v0, v1, s[4:5] offset:1024

; __device__ __forceinline__ void xcd_barrier(const XcdBarrier& b) {
;     ...
;             asm volatile("s_waitcnt vmcnt(0)" ::: "memory");
.LBB0_867:
	s_or_b64 exec, exec, s[12:13]
.LBB0_868:
	s_or_b64 exec, exec, s[4:5]
	s_mov_b64 s[4:5], 0
	s_waitcnt lgkmcnt(0)
	s_barrier

; __device__ __forceinline__ void xcd_barrier(const XcdBarrier& b) {
;     ...
;             asm volatile("s_waitcnt vmcnt(0)" ::: "memory");
.LBB0_1008:
	s_or_b64 exec, exec, s[12:13]
.LBB0_1009:
	s_or_b64 exec, exec, s[4:5]
	s_mov_b64 s[4:5], 0
	s_waitcnt lgkmcnt(0)
	s_barrier

; __device__ __forceinline__ unsigned xb_ld(unsigned* p)              { return __hip_atomic_load(p, __ATOMIC_RELAXED, __HIP_MEMORY_SCOPE_AGENT); }
; __device__ __forceinline__ unsigned xb_add(unsigned* p, unsigned v) { return __hip_atomic_fetch_add(p, v, __ATOMIC_RELAXED, __HIP_MEMORY_SCOPE_AGENT); }
; #define XB_SPIN(cond, bar) do { unsigned _sp = 0; while (cond) { __builtin_amdgcn_s_sleep(1); \
;     if ((++_sp & 255u) == 0u) { if (xb_ld(&(bar)[XB_TMO])) break; if (_sp > XB_SPIN_CAP) { atomicAdd(&(bar)[XB_TMO], 1u); break; } } } } while (0)
; __device__ __forceinline__ void xcd_barrier(const XcdBarrier& b) {
;     ...
;             const unsigned og = xb_add(&bar[XB_TOP], 1u);
;             const unsigned tg = og / nx;
;             if (og + 1u == (tg + 1u) * nx) xb_add(&bar[XB_TOPGEN], 1u);
;             else XB_SPIN(xb_ld(&bar[XB_TOPGEN]) == tg, bar);
;             __builtin_amdgcn_fence(__ATOMIC_ACQUIRE, "agent");
;             xb_add(&bar[XB_XGEN(b.x)], 1u);
;             asm volatile("s_waitcnt vmcnt(0)" ::: "memory");
.LBB0_1209:
	s_or_b64 exec, exec, s[6:7]
	s_mov_b64 s[6:7], exec
	v_mbcnt_lo_u32_b32 v0, s6, 0
	v_mbcnt_hi_u32_b32 v0, s7, v0
	v_cmp_eq_u32_e32 vcc, 0, v0
	s_and_saveexec_b64 s[8:9], vcc
	s_cbranch_execz .LBB0_1211
	s_bcnt1_i32_b64 s6, s[6:7]
	v_mov_b32_e32 v0, 0x2000
	v_mov_b32_e32 v1, s6
	global_atomic_add v0, v1, s[4:5] offset:1024
.LBB0_1211:
	s_or_b64 exec, exec, s[8:9]
.LBB0_1212:
	s_or_b64 exec, exec, s[0:1]
	s_waitcnt lgkmcnt(0)
	s_barrier
